# SSD chunk-output phase: inter-chunk term with the C and state-fragment loads in an 11-slot register ring under counted vmcnt waits (was one vmcnt(0) per load)
# speedup vs baseline: 1.0387x; 1.0083x over previous
.LBB0_850:
	s_mov_b32 s0, 0xb200000
	s_mov_b32 s1, 0
	v_lshl_add_u64 v[232:233], v[166:167], 0, s[0:1]
	global_load_dwordx4 v[48:51], v[232:233], off
	s_mov_b32 s0, 0xb204000
	s_mov_b32 s1, 0
	v_lshl_add_u64 v[234:235], v[166:167], 0, s[0:1]
	global_load_dwordx4 v[52:55], v[234:235], off
	s_mov_b32 s0, 0xb208000
	s_mov_b32 s1, 0
	v_lshl_add_u64 v[236:237], v[166:167], 0, s[0:1]
	global_load_dwordx4 v[56:59], v[236:237], off
	s_mov_b32 s0, 0xb20c000
	s_mov_b32 s1, 0
	v_lshl_add_u64 v[232:233], v[166:167], 0, s[0:1]
	global_load_dwordx4 v[60:63], v[232:233], off
	s_add_u32 vcc_lo, s97, 0
	s_mov_b32 vcc_hi, 0
	v_lshl_add_u64 v[234:235], v[136:137], 0, vcc
	global_load_dwordx4 v[180:183], v[234:235], off
	s_add_u32 vcc_lo, s33, 0
	s_mov_b32 vcc_hi, 0
	v_lshl_add_u64 v[236:237], v[136:137], 0, vcc
	global_load_dwordx4 v[184:187], v[236:237], off
	s_add_u32 vcc_lo, s97, 0
	s_mov_b32 vcc_hi, 0
	v_lshl_add_u64 v[232:233], v[134:135], 0, vcc
	global_load_dwordx4 v[188:191], v[232:233], off
	s_add_u32 vcc_lo, s33, 0
	s_mov_b32 vcc_hi, 0
	v_lshl_add_u64 v[234:235], v[134:135], 0, vcc
	global_load_dwordx4 v[192:195], v[234:235], off
	s_add_u32 vcc_lo, s97, 0
	s_mov_b32 vcc_hi, 0
	v_lshl_add_u64 v[236:237], v[132:133], 0, vcc
	global_load_dwordx4 v[196:199], v[236:237], off
	s_add_u32 vcc_lo, s33, 0
	s_mov_b32 vcc_hi, 0
	v_lshl_add_u64 v[232:233], v[132:133], 0, vcc
	global_load_dwordx4 v[200:203], v[232:233], off
	s_add_u32 vcc_lo, s97, 0
	s_mov_b32 vcc_hi, 0
	v_lshl_add_u64 v[234:235], v[130:131], 0, vcc
	global_load_dwordx4 v[204:207], v[234:235], off
	s_add_u32 vcc_lo, s33, 0
	s_mov_b32 vcc_hi, 0
	v_lshl_add_u64 v[236:237], v[130:131], 0, vcc
	global_load_dwordx4 v[208:211], v[236:237], off
	s_add_u32 vcc_lo, s97, 64
	s_mov_b32 vcc_hi, 0
	v_lshl_add_u64 v[232:233], v[136:137], 0, vcc
	global_load_dwordx4 v[212:215], v[232:233], off
	s_add_u32 vcc_lo, s33, 64
	s_mov_b32 vcc_hi, 0
	v_lshl_add_u64 v[234:235], v[136:137], 0, vcc
	global_load_dwordx4 v[216:219], v[234:235], off
	s_add_u32 vcc_lo, s97, 64
	s_mov_b32 vcc_hi, 0
	v_lshl_add_u64 v[236:237], v[134:135], 0, vcc
	global_load_dwordx4 v[220:223], v[236:237], off
	s_waitcnt vmcnt(11)
	v_lshlrev_b32_e32 v172, 16, v48
	v_and_b32_e32 v173, 0xffff0000, v48
	v_lshlrev_b32_e32 v174, 16, v49
	v_and_b32_e32 v175, 0xffff0000, v49
	v_lshlrev_b32_e32 v176, 16, v50
	v_and_b32_e32 v177, 0xffff0000, v50
	v_lshlrev_b32_e32 v178, 16, v51
	v_and_b32_e32 v179, 0xffff0000, v51
	v_pk_mul_f32 v[48:49], v[108:109], v[172:173]
	v_pk_mul_f32 v[50:51], v[108:109], v[174:175]
	v_pk_mul_f32 v[172:173], v[110:111], v[172:173]
	v_pk_mul_f32 v[174:175], v[110:111], v[174:175]
	v_cvt_pk_bf16_f32 v80, v48, v49
	v_cvt_pk_bf16_f32 v81, v50, v51
	v_cvt_pk_bf16_f32 v96, v172, v173
	v_cvt_pk_bf16_f32 v97, v174, v175
	v_pk_mul_f32 v[48:49], v[108:109], v[176:177]
	v_pk_mul_f32 v[50:51], v[108:109], v[178:179]
	v_pk_mul_f32 v[176:177], v[110:111], v[176:177]
	v_pk_mul_f32 v[178:179], v[110:111], v[178:179]
	v_cvt_pk_bf16_f32 v82, v48, v49
	v_cvt_pk_bf16_f32 v83, v50, v51
	v_cvt_pk_bf16_f32 v98, v176, v177
	v_cvt_pk_bf16_f32 v99, v178, v179
	v_lshlrev_b32_e32 v172, 16, v52
	v_and_b32_e32 v173, 0xffff0000, v52
	v_lshlrev_b32_e32 v174, 16, v53
	v_and_b32_e32 v175, 0xffff0000, v53
	v_lshlrev_b32_e32 v176, 16, v54
	v_and_b32_e32 v177, 0xffff0000, v54
	v_lshlrev_b32_e32 v178, 16, v55
	v_and_b32_e32 v179, 0xffff0000, v55
	v_pk_mul_f32 v[52:53], v[112:113], v[172:173]
	v_pk_mul_f32 v[54:55], v[112:113], v[174:175]
	v_pk_mul_f32 v[172:173], v[114:115], v[172:173]
	v_pk_mul_f32 v[174:175], v[114:115], v[174:175]
	v_cvt_pk_bf16_f32 v84, v52, v53
	v_cvt_pk_bf16_f32 v85, v54, v55
	v_cvt_pk_bf16_f32 v100, v172, v173
	v_cvt_pk_bf16_f32 v101, v174, v175
	v_pk_mul_f32 v[52:53], v[112:113], v[176:177]
	v_pk_mul_f32 v[54:55], v[112:113], v[178:179]
	v_pk_mul_f32 v[176:177], v[114:115], v[176:177]
	v_pk_mul_f32 v[178:179], v[114:115], v[178:179]
	v_cvt_pk_bf16_f32 v86, v52, v53
	v_cvt_pk_bf16_f32 v87, v54, v55
	v_cvt_pk_bf16_f32 v102, v176, v177
	v_cvt_pk_bf16_f32 v103, v178, v179
	v_lshlrev_b32_e32 v172, 16, v56
	v_and_b32_e32 v173, 0xffff0000, v56
	v_lshlrev_b32_e32 v174, 16, v57
	v_and_b32_e32 v175, 0xffff0000, v57
	v_lshlrev_b32_e32 v176, 16, v58
	v_and_b32_e32 v177, 0xffff0000, v58
	v_lshlrev_b32_e32 v178, 16, v59
	v_and_b32_e32 v179, 0xffff0000, v59
	v_pk_mul_f32 v[56:57], v[116:117], v[172:173]
	v_pk_mul_f32 v[58:59], v[116:117], v[174:175]
	v_pk_mul_f32 v[172:173], v[160:161], v[172:173]
	v_pk_mul_f32 v[174:175], v[160:161], v[174:175]
	v_cvt_pk_bf16_f32 v88, v56, v57
	v_cvt_pk_bf16_f32 v89, v58, v59
	v_cvt_pk_bf16_f32 v104, v172, v173
	v_cvt_pk_bf16_f32 v105, v174, v175
	v_pk_mul_f32 v[56:57], v[116:117], v[176:177]
	v_pk_mul_f32 v[58:59], v[116:117], v[178:179]
	v_pk_mul_f32 v[176:177], v[160:161], v[176:177]
	v_pk_mul_f32 v[178:179], v[160:161], v[178:179]
	v_cvt_pk_bf16_f32 v90, v56, v57
	v_cvt_pk_bf16_f32 v91, v58, v59
	v_cvt_pk_bf16_f32 v106, v176, v177
	v_cvt_pk_bf16_f32 v107, v178, v179
	v_lshlrev_b32_e32 v172, 16, v60
	v_and_b32_e32 v173, 0xffff0000, v60
	v_lshlrev_b32_e32 v174, 16, v61
	v_and_b32_e32 v175, 0xffff0000, v61
	v_lshlrev_b32_e32 v176, 16, v62
	v_and_b32_e32 v177, 0xffff0000, v62
	v_lshlrev_b32_e32 v178, 16, v63
	v_and_b32_e32 v179, 0xffff0000, v63
	v_pk_mul_f32 v[60:61], v[162:163], v[172:173]
	v_pk_mul_f32 v[62:63], v[162:163], v[174:175]
	v_pk_mul_f32 v[172:173], v[164:165], v[172:173]
	v_pk_mul_f32 v[174:175], v[164:165], v[174:175]
	v_cvt_pk_bf16_f32 v92, v60, v61
	v_cvt_pk_bf16_f32 v93, v62, v63
	v_cvt_pk_bf16_f32 v168, v172, v173
	v_cvt_pk_bf16_f32 v169, v174, v175
	v_pk_mul_f32 v[60:61], v[162:163], v[176:177]
	v_pk_mul_f32 v[62:63], v[162:163], v[178:179]
	v_pk_mul_f32 v[176:177], v[164:165], v[176:177]
	v_pk_mul_f32 v[178:179], v[164:165], v[178:179]
	v_cvt_pk_bf16_f32 v94, v60, v61
	v_cvt_pk_bf16_f32 v95, v62, v63
	v_cvt_pk_bf16_f32 v170, v176, v177
	v_cvt_pk_bf16_f32 v171, v178, v179
	s_mov_b32 s0, 0xb200040
	s_mov_b32 s1, 0
	v_lshl_add_u64 v[232:233], v[166:167], 0, s[0:1]
	global_load_dwordx4 v[48:51], v[232:233], off
	s_mov_b32 s0, 0xb204040
	s_mov_b32 s1, 0
	v_lshl_add_u64 v[234:235], v[166:167], 0, s[0:1]
	global_load_dwordx4 v[52:55], v[234:235], off
	s_mov_b32 s0, 0xb208040
	s_mov_b32 s1, 0
	v_lshl_add_u64 v[236:237], v[166:167], 0, s[0:1]
	global_load_dwordx4 v[56:59], v[236:237], off
	s_mov_b32 s0, 0xb20c040
	s_mov_b32 s1, 0
	v_lshl_add_u64 v[232:233], v[166:167], 0, s[0:1]
	global_load_dwordx4 v[60:63], v[232:233], off
	s_waitcnt vmcnt(14)
	v_mfma_f32_16x16x32_bf16 v[72:75], v[180:183], v[80:83], v[72:75]
	v_mfma_f32_16x16x32_bf16 v[36:39], v[180:183], v[84:87], v[36:39]
	v_mfma_f32_16x16x32_bf16 v[8:11], v[180:183], v[88:91], v[8:11]
	v_mfma_f32_16x16x32_bf16 v[28:31], v[180:183], v[92:95], v[28:31]
	s_add_u32 vcc_lo, s33, 64
	s_mov_b32 vcc_hi, 0
	v_lshl_add_u64 v[234:235], v[134:135], 0, vcc
	global_load_dwordx4 v[180:183], v[234:235], off
	s_waitcnt vmcnt(14)
	v_mfma_f32_16x16x32_bf16 v[72:75], v[184:187], v[96:99], v[72:75]
	v_mfma_f32_16x16x32_bf16 v[36:39], v[184:187], v[100:103], v[36:39]
	v_mfma_f32_16x16x32_bf16 v[8:11], v[184:187], v[104:107], v[8:11]
	v_mfma_f32_16x16x32_bf16 v[28:31], v[184:187], v[168:171], v[28:31]
	s_add_u32 vcc_lo, s97, 64
	s_mov_b32 vcc_hi, 0
	v_lshl_add_u64 v[236:237], v[132:133], 0, vcc
	global_load_dwordx4 v[184:187], v[236:237], off
	s_waitcnt vmcnt(14)
	v_mfma_f32_16x16x32_bf16 v[76:79], v[188:191], v[80:83], v[76:79]
	v_mfma_f32_16x16x32_bf16 v[44:47], v[188:191], v[84:87], v[44:47]
	v_mfma_f32_16x16x32_bf16 v[12:15], v[188:191], v[88:91], v[12:15]
	v_mfma_f32_16x16x32_bf16 v[40:43], v[188:191], v[92:95], v[40:43]
	s_add_u32 vcc_lo, s33, 64
	s_mov_b32 vcc_hi, 0
	v_lshl_add_u64 v[232:233], v[132:133], 0, vcc
	global_load_dwordx4 v[188:191], v[232:233], off
	s_waitcnt vmcnt(14)
	v_mfma_f32_16x16x32_bf16 v[76:79], v[192:195], v[96:99], v[76:79]
	v_mfma_f32_16x16x32_bf16 v[44:47], v[192:195], v[100:103], v[44:47]
	v_mfma_f32_16x16x32_bf16 v[12:15], v[192:195], v[104:107], v[12:15]
	v_mfma_f32_16x16x32_bf16 v[40:43], v[192:195], v[168:171], v[40:43]
	s_add_u32 vcc_lo, s97, 64
	s_mov_b32 vcc_hi, 0
	v_lshl_add_u64 v[234:235], v[130:131], 0, vcc
	global_load_dwordx4 v[192:195], v[234:235], off
	s_waitcnt vmcnt(14)
	v_mfma_f32_16x16x32_bf16 v[64:67], v[196:199], v[80:83], v[64:67]
	v_mfma_f32_16x16x32_bf16 v[20:23], v[196:199], v[84:87], v[20:23]
	v_mfma_f32_16x16x32_bf16 v[0:3], v[196:199], v[88:91], v[0:3]
	v_mfma_f32_16x16x32_bf16 v[16:19], v[196:199], v[92:95], v[16:19]
	s_add_u32 vcc_lo, s33, 64
	s_mov_b32 vcc_hi, 0
	v_lshl_add_u64 v[236:237], v[130:131], 0, vcc
	global_load_dwordx4 v[196:199], v[236:237], off
	s_waitcnt vmcnt(14)
	v_mfma_f32_16x16x32_bf16 v[64:67], v[200:203], v[96:99], v[64:67]
	v_mfma_f32_16x16x32_bf16 v[20:23], v[200:203], v[100:103], v[20:23]
	v_mfma_f32_16x16x32_bf16 v[0:3], v[200:203], v[104:107], v[0:3]
	v_mfma_f32_16x16x32_bf16 v[16:19], v[200:203], v[168:171], v[16:19]
	s_add_u32 vcc_lo, s97, 128
	s_mov_b32 vcc_hi, 0
	v_lshl_add_u64 v[232:233], v[136:137], 0, vcc
	global_load_dwordx4 v[200:203], v[232:233], off
	s_waitcnt vmcnt(14)
	v_mfma_f32_16x16x32_bf16 v[68:71], v[204:207], v[80:83], v[68:71]
	v_mfma_f32_16x16x32_bf16 v[32:35], v[204:207], v[84:87], v[32:35]
	v_mfma_f32_16x16x32_bf16 v[4:7], v[204:207], v[88:91], v[4:7]
	v_mfma_f32_16x16x32_bf16 v[24:27], v[204:207], v[92:95], v[24:27]
	s_add_u32 vcc_lo, s33, 128
	s_mov_b32 vcc_hi, 0
	v_lshl_add_u64 v[234:235], v[136:137], 0, vcc
	global_load_dwordx4 v[204:207], v[234:235], off
	s_waitcnt vmcnt(14)
	v_mfma_f32_16x16x32_bf16 v[68:71], v[208:211], v[96:99], v[68:71]
	v_mfma_f32_16x16x32_bf16 v[32:35], v[208:211], v[100:103], v[32:35]
	v_mfma_f32_16x16x32_bf16 v[4:7], v[208:211], v[104:107], v[4:7]
	v_mfma_f32_16x16x32_bf16 v[24:27], v[208:211], v[168:171], v[24:27]
	s_add_u32 vcc_lo, s97, 128
	s_mov_b32 vcc_hi, 0
	v_lshl_add_u64 v[236:237], v[134:135], 0, vcc
	global_load_dwordx4 v[208:211], v[236:237], off
	s_waitcnt vmcnt(8)
	v_lshlrev_b32_e32 v172, 16, v48
	v_and_b32_e32 v173, 0xffff0000, v48
	v_lshlrev_b32_e32 v174, 16, v49
	v_and_b32_e32 v175, 0xffff0000, v49
	v_lshlrev_b32_e32 v176, 16, v50
	v_and_b32_e32 v177, 0xffff0000, v50
	v_lshlrev_b32_e32 v178, 16, v51
	v_and_b32_e32 v179, 0xffff0000, v51
	v_pk_mul_f32 v[48:49], v[108:109], v[172:173]
	v_pk_mul_f32 v[50:51], v[108:109], v[174:175]
	v_pk_mul_f32 v[172:173], v[110:111], v[172:173]
	v_pk_mul_f32 v[174:175], v[110:111], v[174:175]
	v_cvt_pk_bf16_f32 v80, v48, v49
	v_cvt_pk_bf16_f32 v81, v50, v51
	v_cvt_pk_bf16_f32 v96, v172, v173
	v_cvt_pk_bf16_f32 v97, v174, v175
	v_pk_mul_f32 v[48:49], v[108:109], v[176:177]
	v_pk_mul_f32 v[50:51], v[108:109], v[178:179]
	v_pk_mul_f32 v[176:177], v[110:111], v[176:177]
	v_pk_mul_f32 v[178:179], v[110:111], v[178:179]
	v_cvt_pk_bf16_f32 v82, v48, v49
	v_cvt_pk_bf16_f32 v83, v50, v51
	v_cvt_pk_bf16_f32 v98, v176, v177
	v_cvt_pk_bf16_f32 v99, v178, v179
	v_lshlrev_b32_e32 v172, 16, v52
	v_and_b32_e32 v173, 0xffff0000, v52
	v_lshlrev_b32_e32 v174, 16, v53
	v_and_b32_e32 v175, 0xffff0000, v53
	v_lshlrev_b32_e32 v176, 16, v54
	v_and_b32_e32 v177, 0xffff0000, v54
	v_lshlrev_b32_e32 v178, 16, v55
	v_and_b32_e32 v179, 0xffff0000, v55
	v_pk_mul_f32 v[52:53], v[112:113], v[172:173]
	v_pk_mul_f32 v[54:55], v[112:113], v[174:175]
	v_pk_mul_f32 v[172:173], v[114:115], v[172:173]
	v_pk_mul_f32 v[174:175], v[114:115], v[174:175]
	v_cvt_pk_bf16_f32 v84, v52, v53
	v_cvt_pk_bf16_f32 v85, v54, v55
	v_cvt_pk_bf16_f32 v100, v172, v173
	v_cvt_pk_bf16_f32 v101, v174, v175
	v_pk_mul_f32 v[52:53], v[112:113], v[176:177]
	v_pk_mul_f32 v[54:55], v[112:113], v[178:179]
	v_pk_mul_f32 v[176:177], v[114:115], v[176:177]
	v_pk_mul_f32 v[178:179], v[114:115], v[178:179]
	v_cvt_pk_bf16_f32 v86, v52, v53
	v_cvt_pk_bf16_f32 v87, v54, v55
	v_cvt_pk_bf16_f32 v102, v176, v177
	v_cvt_pk_bf16_f32 v103, v178, v179
	v_lshlrev_b32_e32 v172, 16, v56
	v_and_b32_e32 v173, 0xffff0000, v56
	v_lshlrev_b32_e32 v174, 16, v57
	v_and_b32_e32 v175, 0xffff0000, v57
	v_lshlrev_b32_e32 v176, 16, v58
	v_and_b32_e32 v177, 0xffff0000, v58
	v_lshlrev_b32_e32 v178, 16, v59
	v_and_b32_e32 v179, 0xffff0000, v59
	v_pk_mul_f32 v[56:57], v[116:117], v[172:173]
	v_pk_mul_f32 v[58:59], v[116:117], v[174:175]
	v_pk_mul_f32 v[172:173], v[160:161], v[172:173]
	v_pk_mul_f32 v[174:175], v[160:161], v[174:175]
	v_cvt_pk_bf16_f32 v88, v56, v57
	v_cvt_pk_bf16_f32 v89, v58, v59
	v_cvt_pk_bf16_f32 v104, v172, v173
	v_cvt_pk_bf16_f32 v105, v174, v175
	v_pk_mul_f32 v[56:57], v[116:117], v[176:177]
	v_pk_mul_f32 v[58:59], v[116:117], v[178:179]
	v_pk_mul_f32 v[176:177], v[160:161], v[176:177]
	v_pk_mul_f32 v[178:179], v[160:161], v[178:179]
	v_cvt_pk_bf16_f32 v90, v56, v57
	v_cvt_pk_bf16_f32 v91, v58, v59
	v_cvt_pk_bf16_f32 v106, v176, v177
	v_cvt_pk_bf16_f32 v107, v178, v179
	v_lshlrev_b32_e32 v172, 16, v60
	v_and_b32_e32 v173, 0xffff0000, v60
	v_lshlrev_b32_e32 v174, 16, v61
	v_and_b32_e32 v175, 0xffff0000, v61
	v_lshlrev_b32_e32 v176, 16, v62
	v_and_b32_e32 v177, 0xffff0000, v62
	v_lshlrev_b32_e32 v178, 16, v63
	v_and_b32_e32 v179, 0xffff0000, v63
	v_pk_mul_f32 v[60:61], v[162:163], v[172:173]
	v_pk_mul_f32 v[62:63], v[162:163], v[174:175]
	v_pk_mul_f32 v[172:173], v[164:165], v[172:173]
	v_pk_mul_f32 v[174:175], v[164:165], v[174:175]
	v_cvt_pk_bf16_f32 v92, v60, v61
	v_cvt_pk_bf16_f32 v93, v62, v63
	v_cvt_pk_bf16_f32 v168, v172, v173
	v_cvt_pk_bf16_f32 v169, v174, v175
	v_pk_mul_f32 v[60:61], v[162:163], v[176:177]
	v_pk_mul_f32 v[62:63], v[162:163], v[178:179]
	v_pk_mul_f32 v[176:177], v[164:165], v[176:177]
	v_pk_mul_f32 v[178:179], v[164:165], v[178:179]
	v_cvt_pk_bf16_f32 v94, v60, v61
	v_cvt_pk_bf16_f32 v95, v62, v63
	v_cvt_pk_bf16_f32 v170, v176, v177
	v_cvt_pk_bf16_f32 v171, v178, v179
	s_mov_b32 s0, 0xb200080
	s_mov_b32 s1, 0
	v_lshl_add_u64 v[232:233], v[166:167], 0, s[0:1]
	global_load_dwordx4 v[48:51], v[232:233], off
	s_mov_b32 s0, 0xb204080
	s_mov_b32 s1, 0
	v_lshl_add_u64 v[234:235], v[166:167], 0, s[0:1]
	global_load_dwordx4 v[52:55], v[234:235], off
	s_mov_b32 s0, 0xb208080
	s_mov_b32 s1, 0
	v_lshl_add_u64 v[236:237], v[166:167], 0, s[0:1]
	global_load_dwordx4 v[56:59], v[236:237], off
	s_mov_b32 s0, 0xb20c080
	s_mov_b32 s1, 0
	v_lshl_add_u64 v[232:233], v[166:167], 0, s[0:1]
	global_load_dwordx4 v[60:63], v[232:233], off
	s_waitcnt vmcnt(18)
	v_mfma_f32_16x16x32_bf16 v[72:75], v[212:215], v[80:83], v[72:75]
	v_mfma_f32_16x16x32_bf16 v[36:39], v[212:215], v[84:87], v[36:39]
	v_mfma_f32_16x16x32_bf16 v[8:11], v[212:215], v[88:91], v[8:11]
	v_mfma_f32_16x16x32_bf16 v[28:31], v[212:215], v[92:95], v[28:31]
	s_add_u32 vcc_lo, s33, 128
	s_mov_b32 vcc_hi, 0
	v_lshl_add_u64 v[234:235], v[134:135], 0, vcc
	global_load_dwordx4 v[212:215], v[234:235], off
	s_waitcnt vmcnt(18)
	v_mfma_f32_16x16x32_bf16 v[72:75], v[216:219], v[96:99], v[72:75]
	v_mfma_f32_16x16x32_bf16 v[36:39], v[216:219], v[100:103], v[36:39]
	v_mfma_f32_16x16x32_bf16 v[8:11], v[216:219], v[104:107], v[8:11]
	v_mfma_f32_16x16x32_bf16 v[28:31], v[216:219], v[168:171], v[28:31]
	s_add_u32 vcc_lo, s97, 128
	s_mov_b32 vcc_hi, 0
	v_lshl_add_u64 v[236:237], v[132:133], 0, vcc
	global_load_dwordx4 v[216:219], v[236:237], off
	s_waitcnt vmcnt(18)
	v_mfma_f32_16x16x32_bf16 v[76:79], v[220:223], v[80:83], v[76:79]
	v_mfma_f32_16x16x32_bf16 v[44:47], v[220:223], v[84:87], v[44:47]
	v_mfma_f32_16x16x32_bf16 v[12:15], v[220:223], v[88:91], v[12:15]
	v_mfma_f32_16x16x32_bf16 v[40:43], v[220:223], v[92:95], v[40:43]
	s_add_u32 vcc_lo, s33, 128
	s_mov_b32 vcc_hi, 0
	v_lshl_add_u64 v[232:233], v[132:133], 0, vcc
	global_load_dwordx4 v[220:223], v[232:233], off
	s_waitcnt vmcnt(14)
	v_mfma_f32_16x16x32_bf16 v[76:79], v[180:183], v[96:99], v[76:79]
	v_mfma_f32_16x16x32_bf16 v[44:47], v[180:183], v[100:103], v[44:47]
	v_mfma_f32_16x16x32_bf16 v[12:15], v[180:183], v[104:107], v[12:15]
	v_mfma_f32_16x16x32_bf16 v[40:43], v[180:183], v[168:171], v[40:43]
	s_add_u32 vcc_lo, s97, 128
	s_mov_b32 vcc_hi, 0
	v_lshl_add_u64 v[234:235], v[130:131], 0, vcc
	global_load_dwordx4 v[180:183], v[234:235], off
	s_waitcnt vmcnt(14)
	v_mfma_f32_16x16x32_bf16 v[64:67], v[184:187], v[80:83], v[64:67]
	v_mfma_f32_16x16x32_bf16 v[20:23], v[184:187], v[84:87], v[20:23]
	v_mfma_f32_16x16x32_bf16 v[0:3], v[184:187], v[88:91], v[0:3]
	v_mfma_f32_16x16x32_bf16 v[16:19], v[184:187], v[92:95], v[16:19]
	s_add_u32 vcc_lo, s33, 128
	s_mov_b32 vcc_hi, 0
	v_lshl_add_u64 v[236:237], v[130:131], 0, vcc
	global_load_dwordx4 v[184:187], v[236:237], off
	s_waitcnt vmcnt(14)
	v_mfma_f32_16x16x32_bf16 v[64:67], v[188:191], v[96:99], v[64:67]
	v_mfma_f32_16x16x32_bf16 v[20:23], v[188:191], v[100:103], v[20:23]
	v_mfma_f32_16x16x32_bf16 v[0:3], v[188:191], v[104:107], v[0:3]
	v_mfma_f32_16x16x32_bf16 v[16:19], v[188:191], v[168:171], v[16:19]
	s_add_u32 vcc_lo, s97, 192
	s_mov_b32 vcc_hi, 0
	v_lshl_add_u64 v[232:233], v[136:137], 0, vcc
	global_load_dwordx4 v[188:191], v[232:233], off
	s_waitcnt vmcnt(14)
	v_mfma_f32_16x16x32_bf16 v[68:71], v[192:195], v[80:83], v[68:71]
	v_mfma_f32_16x16x32_bf16 v[32:35], v[192:195], v[84:87], v[32:35]
	v_mfma_f32_16x16x32_bf16 v[4:7], v[192:195], v[88:91], v[4:7]
	v_mfma_f32_16x16x32_bf16 v[24:27], v[192:195], v[92:95], v[24:27]
	s_add_u32 vcc_lo, s33, 192
	s_mov_b32 vcc_hi, 0
	v_lshl_add_u64 v[234:235], v[136:137], 0, vcc
	global_load_dwordx4 v[192:195], v[234:235], off
	s_waitcnt vmcnt(14)
	v_mfma_f32_16x16x32_bf16 v[68:71], v[196:199], v[96:99], v[68:71]
	v_mfma_f32_16x16x32_bf16 v[32:35], v[196:199], v[100:103], v[32:35]
	v_mfma_f32_16x16x32_bf16 v[4:7], v[196:199], v[104:107], v[4:7]
	v_mfma_f32_16x16x32_bf16 v[24:27], v[196:199], v[168:171], v[24:27]
	s_add_u32 vcc_lo, s97, 192
	s_mov_b32 vcc_hi, 0
	v_lshl_add_u64 v[236:237], v[134:135], 0, vcc
	global_load_dwordx4 v[196:199], v[236:237], off
	s_waitcnt vmcnt(8)
	v_lshlrev_b32_e32 v172, 16, v48
	v_and_b32_e32 v173, 0xffff0000, v48
	v_lshlrev_b32_e32 v174, 16, v49
	v_and_b32_e32 v175, 0xffff0000, v49
	v_lshlrev_b32_e32 v176, 16, v50
	v_and_b32_e32 v177, 0xffff0000, v50
	v_lshlrev_b32_e32 v178, 16, v51
	v_and_b32_e32 v179, 0xffff0000, v51
	v_pk_mul_f32 v[48:49], v[108:109], v[172:173]
	v_pk_mul_f32 v[50:51], v[108:109], v[174:175]
	v_pk_mul_f32 v[172:173], v[110:111], v[172:173]
	v_pk_mul_f32 v[174:175], v[110:111], v[174:175]
	v_cvt_pk_bf16_f32 v80, v48, v49
	v_cvt_pk_bf16_f32 v81, v50, v51
	v_cvt_pk_bf16_f32 v96, v172, v173
	v_cvt_pk_bf16_f32 v97, v174, v175
	v_pk_mul_f32 v[48:49], v[108:109], v[176:177]
	v_pk_mul_f32 v[50:51], v[108:109], v[178:179]
	v_pk_mul_f32 v[176:177], v[110:111], v[176:177]
	v_pk_mul_f32 v[178:179], v[110:111], v[178:179]
	v_cvt_pk_bf16_f32 v82, v48, v49
	v_cvt_pk_bf16_f32 v83, v50, v51
	v_cvt_pk_bf16_f32 v98, v176, v177
	v_cvt_pk_bf16_f32 v99, v178, v179
	v_lshlrev_b32_e32 v172, 16, v52
	v_and_b32_e32 v173, 0xffff0000, v52
	v_lshlrev_b32_e32 v174, 16, v53
	v_and_b32_e32 v175, 0xffff0000, v53
	v_lshlrev_b32_e32 v176, 16, v54
	v_and_b32_e32 v177, 0xffff0000, v54
	v_lshlrev_b32_e32 v178, 16, v55
	v_and_b32_e32 v179, 0xffff0000, v55
	v_pk_mul_f32 v[52:53], v[112:113], v[172:173]
	v_pk_mul_f32 v[54:55], v[112:113], v[174:175]
	v_pk_mul_f32 v[172:173], v[114:115], v[172:173]
	v_pk_mul_f32 v[174:175], v[114:115], v[174:175]
	v_cvt_pk_bf16_f32 v84, v52, v53
	v_cvt_pk_bf16_f32 v85, v54, v55
	v_cvt_pk_bf16_f32 v100, v172, v173
	v_cvt_pk_bf16_f32 v101, v174, v175
	v_pk_mul_f32 v[52:53], v[112:113], v[176:177]
	v_pk_mul_f32 v[54:55], v[112:113], v[178:179]
	v_pk_mul_f32 v[176:177], v[114:115], v[176:177]
	v_pk_mul_f32 v[178:179], v[114:115], v[178:179]
	v_cvt_pk_bf16_f32 v86, v52, v53
	v_cvt_pk_bf16_f32 v87, v54, v55
	v_cvt_pk_bf16_f32 v102, v176, v177
	v_cvt_pk_bf16_f32 v103, v178, v179
	v_lshlrev_b32_e32 v172, 16, v56
	v_and_b32_e32 v173, 0xffff0000, v56
	v_lshlrev_b32_e32 v174, 16, v57
	v_and_b32_e32 v175, 0xffff0000, v57
	v_lshlrev_b32_e32 v176, 16, v58
	v_and_b32_e32 v177, 0xffff0000, v58
	v_lshlrev_b32_e32 v178, 16, v59
	v_and_b32_e32 v179, 0xffff0000, v59
	v_pk_mul_f32 v[56:57], v[116:117], v[172:173]
	v_pk_mul_f32 v[58:59], v[116:117], v[174:175]
	v_pk_mul_f32 v[172:173], v[160:161], v[172:173]
	v_pk_mul_f32 v[174:175], v[160:161], v[174:175]
	v_cvt_pk_bf16_f32 v88, v56, v57
	v_cvt_pk_bf16_f32 v89, v58, v59
	v_cvt_pk_bf16_f32 v104, v172, v173
	v_cvt_pk_bf16_f32 v105, v174, v175
	v_pk_mul_f32 v[56:57], v[116:117], v[176:177]
	v_pk_mul_f32 v[58:59], v[116:117], v[178:179]
	v_pk_mul_f32 v[176:177], v[160:161], v[176:177]
	v_pk_mul_f32 v[178:179], v[160:161], v[178:179]
	v_cvt_pk_bf16_f32 v90, v56, v57
	v_cvt_pk_bf16_f32 v91, v58, v59
	v_cvt_pk_bf16_f32 v106, v176, v177
	v_cvt_pk_bf16_f32 v107, v178, v179
	v_lshlrev_b32_e32 v172, 16, v60
	v_and_b32_e32 v173, 0xffff0000, v60
	v_lshlrev_b32_e32 v174, 16, v61
	v_and_b32_e32 v175, 0xffff0000, v61
	v_lshlrev_b32_e32 v176, 16, v62
	v_and_b32_e32 v177, 0xffff0000, v62
	v_lshlrev_b32_e32 v178, 16, v63
	v_and_b32_e32 v179, 0xffff0000, v63
	v_pk_mul_f32 v[60:61], v[162:163], v[172:173]
	v_pk_mul_f32 v[62:63], v[162:163], v[174:175]
	v_pk_mul_f32 v[172:173], v[164:165], v[172:173]
	v_pk_mul_f32 v[174:175], v[164:165], v[174:175]
	v_cvt_pk_bf16_f32 v92, v60, v61
	v_cvt_pk_bf16_f32 v93, v62, v63
	v_cvt_pk_bf16_f32 v168, v172, v173
	v_cvt_pk_bf16_f32 v169, v174, v175
	v_pk_mul_f32 v[60:61], v[162:163], v[176:177]
	v_pk_mul_f32 v[62:63], v[162:163], v[178:179]
	v_pk_mul_f32 v[176:177], v[164:165], v[176:177]
	v_pk_mul_f32 v[178:179], v[164:165], v[178:179]
	v_cvt_pk_bf16_f32 v94, v60, v61
	v_cvt_pk_bf16_f32 v95, v62, v63
	v_cvt_pk_bf16_f32 v170, v176, v177
	v_cvt_pk_bf16_f32 v171, v178, v179
	s_mov_b32 s0, 0xb2000c0
	s_mov_b32 s1, 0
	v_lshl_add_u64 v[232:233], v[166:167], 0, s[0:1]
	global_load_dwordx4 v[48:51], v[232:233], off
	s_mov_b32 s0, 0xb2040c0
	s_mov_b32 s1, 0
	v_lshl_add_u64 v[234:235], v[166:167], 0, s[0:1]
	global_load_dwordx4 v[52:55], v[234:235], off
	s_mov_b32 s0, 0xb2080c0
	s_mov_b32 s1, 0
	v_lshl_add_u64 v[236:237], v[166:167], 0, s[0:1]
	global_load_dwordx4 v[56:59], v[236:237], off
	s_mov_b32 s0, 0xb20c0c0
	s_mov_b32 s1, 0
	v_lshl_add_u64 v[232:233], v[166:167], 0, s[0:1]
	global_load_dwordx4 v[60:63], v[232:233], off
	s_waitcnt vmcnt(18)
	v_mfma_f32_16x16x32_bf16 v[72:75], v[200:203], v[80:83], v[72:75]
	v_mfma_f32_16x16x32_bf16 v[36:39], v[200:203], v[84:87], v[36:39]
	v_mfma_f32_16x16x32_bf16 v[8:11], v[200:203], v[88:91], v[8:11]
	v_mfma_f32_16x16x32_bf16 v[28:31], v[200:203], v[92:95], v[28:31]
	s_add_u32 vcc_lo, s33, 192
	s_mov_b32 vcc_hi, 0
	v_lshl_add_u64 v[234:235], v[134:135], 0, vcc
	global_load_dwordx4 v[200:203], v[234:235], off
	s_waitcnt vmcnt(18)
	v_mfma_f32_16x16x32_bf16 v[72:75], v[204:207], v[96:99], v[72:75]
	v_mfma_f32_16x16x32_bf16 v[36:39], v[204:207], v[100:103], v[36:39]
	v_mfma_f32_16x16x32_bf16 v[8:11], v[204:207], v[104:107], v[8:11]
	v_mfma_f32_16x16x32_bf16 v[28:31], v[204:207], v[168:171], v[28:31]
	s_add_u32 vcc_lo, s97, 192
	s_mov_b32 vcc_hi, 0
	v_lshl_add_u64 v[236:237], v[132:133], 0, vcc
	global_load_dwordx4 v[204:207], v[236:237], off
	s_waitcnt vmcnt(18)
	v_mfma_f32_16x16x32_bf16 v[76:79], v[208:211], v[80:83], v[76:79]
	v_mfma_f32_16x16x32_bf16 v[44:47], v[208:211], v[84:87], v[44:47]
	v_mfma_f32_16x16x32_bf16 v[12:15], v[208:211], v[88:91], v[12:15]
	v_mfma_f32_16x16x32_bf16 v[40:43], v[208:211], v[92:95], v[40:43]
	s_add_u32 vcc_lo, s33, 192
	s_mov_b32 vcc_hi, 0
	v_lshl_add_u64 v[232:233], v[132:133], 0, vcc
	global_load_dwordx4 v[208:211], v[232:233], off
	s_waitcnt vmcnt(14)
	v_mfma_f32_16x16x32_bf16 v[76:79], v[212:215], v[96:99], v[76:79]
	v_mfma_f32_16x16x32_bf16 v[44:47], v[212:215], v[100:103], v[44:47]
	v_mfma_f32_16x16x32_bf16 v[12:15], v[212:215], v[104:107], v[12:15]
	v_mfma_f32_16x16x32_bf16 v[40:43], v[212:215], v[168:171], v[40:43]
	s_add_u32 vcc_lo, s97, 192
	s_mov_b32 vcc_hi, 0
	v_lshl_add_u64 v[234:235], v[130:131], 0, vcc
	global_load_dwordx4 v[212:215], v[234:235], off
	s_waitcnt vmcnt(14)
	v_mfma_f32_16x16x32_bf16 v[64:67], v[216:219], v[80:83], v[64:67]
	v_mfma_f32_16x16x32_bf16 v[20:23], v[216:219], v[84:87], v[20:23]
	v_mfma_f32_16x16x32_bf16 v[0:3], v[216:219], v[88:91], v[0:3]
	v_mfma_f32_16x16x32_bf16 v[16:19], v[216:219], v[92:95], v[16:19]
	s_add_u32 vcc_lo, s33, 192
	s_mov_b32 vcc_hi, 0
	v_lshl_add_u64 v[236:237], v[130:131], 0, vcc
	global_load_dwordx4 v[216:219], v[236:237], off
	s_waitcnt vmcnt(14)
	v_mfma_f32_16x16x32_bf16 v[64:67], v[220:223], v[96:99], v[64:67]
	v_mfma_f32_16x16x32_bf16 v[20:23], v[220:223], v[100:103], v[20:23]
	v_mfma_f32_16x16x32_bf16 v[0:3], v[220:223], v[104:107], v[0:3]
	v_mfma_f32_16x16x32_bf16 v[16:19], v[220:223], v[168:171], v[16:19]
	s_waitcnt vmcnt(13)
	v_mfma_f32_16x16x32_bf16 v[68:71], v[180:183], v[80:83], v[68:71]
	v_mfma_f32_16x16x32_bf16 v[32:35], v[180:183], v[84:87], v[32:35]
	v_mfma_f32_16x16x32_bf16 v[4:7], v[180:183], v[88:91], v[4:7]
	v_mfma_f32_16x16x32_bf16 v[24:27], v[180:183], v[92:95], v[24:27]
	s_waitcnt vmcnt(12)
	v_mfma_f32_16x16x32_bf16 v[68:71], v[184:187], v[96:99], v[68:71]
	v_mfma_f32_16x16x32_bf16 v[32:35], v[184:187], v[100:103], v[32:35]
	v_mfma_f32_16x16x32_bf16 v[4:7], v[184:187], v[104:107], v[4:7]
	v_mfma_f32_16x16x32_bf16 v[24:27], v[184:187], v[168:171], v[24:27]
	s_waitcnt vmcnt(5)
	v_lshlrev_b32_e32 v172, 16, v48
	v_and_b32_e32 v173, 0xffff0000, v48
	v_lshlrev_b32_e32 v174, 16, v49
	v_and_b32_e32 v175, 0xffff0000, v49
	v_lshlrev_b32_e32 v176, 16, v50
	v_and_b32_e32 v177, 0xffff0000, v50
	v_lshlrev_b32_e32 v178, 16, v51
	v_and_b32_e32 v179, 0xffff0000, v51
	v_pk_mul_f32 v[48:49], v[108:109], v[172:173]
	v_pk_mul_f32 v[50:51], v[108:109], v[174:175]
	v_pk_mul_f32 v[172:173], v[110:111], v[172:173]
	v_pk_mul_f32 v[174:175], v[110:111], v[174:175]
	v_cvt_pk_bf16_f32 v80, v48, v49
	v_cvt_pk_bf16_f32 v81, v50, v51
	v_cvt_pk_bf16_f32 v96, v172, v173
	v_cvt_pk_bf16_f32 v97, v174, v175
	v_pk_mul_f32 v[48:49], v[108:109], v[176:177]
	v_pk_mul_f32 v[50:51], v[108:109], v[178:179]
	v_pk_mul_f32 v[176:177], v[110:111], v[176:177]
	v_pk_mul_f32 v[178:179], v[110:111], v[178:179]
	v_cvt_pk_bf16_f32 v82, v48, v49
	v_cvt_pk_bf16_f32 v83, v50, v51
	v_cvt_pk_bf16_f32 v98, v176, v177
	v_cvt_pk_bf16_f32 v99, v178, v179
	v_lshlrev_b32_e32 v172, 16, v52
	v_and_b32_e32 v173, 0xffff0000, v52
	v_lshlrev_b32_e32 v174, 16, v53
	v_and_b32_e32 v175, 0xffff0000, v53
	v_lshlrev_b32_e32 v176, 16, v54
	v_and_b32_e32 v177, 0xffff0000, v54
	v_lshlrev_b32_e32 v178, 16, v55
	v_and_b32_e32 v179, 0xffff0000, v55
	v_pk_mul_f32 v[52:53], v[112:113], v[172:173]
	v_pk_mul_f32 v[54:55], v[112:113], v[174:175]
	v_pk_mul_f32 v[172:173], v[114:115], v[172:173]
	v_pk_mul_f32 v[174:175], v[114:115], v[174:175]
	v_cvt_pk_bf16_f32 v84, v52, v53
	v_cvt_pk_bf16_f32 v85, v54, v55
	v_cvt_pk_bf16_f32 v100, v172, v173
	v_cvt_pk_bf16_f32 v101, v174, v175
	v_pk_mul_f32 v[52:53], v[112:113], v[176:177]
	v_pk_mul_f32 v[54:55], v[112:113], v[178:179]
	v_pk_mul_f32 v[176:177], v[114:115], v[176:177]
	v_pk_mul_f32 v[178:179], v[114:115], v[178:179]
	v_cvt_pk_bf16_f32 v86, v52, v53
	v_cvt_pk_bf16_f32 v87, v54, v55
	v_cvt_pk_bf16_f32 v102, v176, v177
	v_cvt_pk_bf16_f32 v103, v178, v179
	v_lshlrev_b32_e32 v172, 16, v56
	v_and_b32_e32 v173, 0xffff0000, v56
	v_lshlrev_b32_e32 v174, 16, v57
	v_and_b32_e32 v175, 0xffff0000, v57
	v_lshlrev_b32_e32 v176, 16, v58
	v_and_b32_e32 v177, 0xffff0000, v58
	v_lshlrev_b32_e32 v178, 16, v59
	v_and_b32_e32 v179, 0xffff0000, v59
	v_pk_mul_f32 v[56:57], v[116:117], v[172:173]
	v_pk_mul_f32 v[58:59], v[116:117], v[174:175]
	v_pk_mul_f32 v[172:173], v[160:161], v[172:173]
	v_pk_mul_f32 v[174:175], v[160:161], v[174:175]
	v_cvt_pk_bf16_f32 v88, v56, v57
	v_cvt_pk_bf16_f32 v89, v58, v59
	v_cvt_pk_bf16_f32 v104, v172, v173
	v_cvt_pk_bf16_f32 v105, v174, v175
	v_pk_mul_f32 v[56:57], v[116:117], v[176:177]
	v_pk_mul_f32 v[58:59], v[116:117], v[178:179]
	v_pk_mul_f32 v[176:177], v[160:161], v[176:177]
	v_pk_mul_f32 v[178:179], v[160:161], v[178:179]
	v_cvt_pk_bf16_f32 v90, v56, v57
	v_cvt_pk_bf16_f32 v91, v58, v59
	v_cvt_pk_bf16_f32 v106, v176, v177
	v_cvt_pk_bf16_f32 v107, v178, v179
	v_lshlrev_b32_e32 v172, 16, v60
	v_and_b32_e32 v173, 0xffff0000, v60
	v_lshlrev_b32_e32 v174, 16, v61
	v_and_b32_e32 v175, 0xffff0000, v61
	v_lshlrev_b32_e32 v176, 16, v62
	v_and_b32_e32 v177, 0xffff0000, v62
	v_lshlrev_b32_e32 v178, 16, v63
	v_and_b32_e32 v179, 0xffff0000, v63
	v_pk_mul_f32 v[60:61], v[162:163], v[172:173]
	v_pk_mul_f32 v[62:63], v[162:163], v[174:175]
	v_pk_mul_f32 v[172:173], v[164:165], v[172:173]
	v_pk_mul_f32 v[174:175], v[164:165], v[174:175]
	v_cvt_pk_bf16_f32 v92, v60, v61
	v_cvt_pk_bf16_f32 v93, v62, v63
	v_cvt_pk_bf16_f32 v168, v172, v173
	v_cvt_pk_bf16_f32 v169, v174, v175
	v_pk_mul_f32 v[60:61], v[162:163], v[176:177]
	v_pk_mul_f32 v[62:63], v[162:163], v[178:179]
	v_pk_mul_f32 v[176:177], v[164:165], v[176:177]
	v_pk_mul_f32 v[178:179], v[164:165], v[178:179]
	v_cvt_pk_bf16_f32 v94, v60, v61
	v_cvt_pk_bf16_f32 v95, v62, v63
	v_cvt_pk_bf16_f32 v170, v176, v177
	v_cvt_pk_bf16_f32 v171, v178, v179
	s_nop 1
	s_waitcnt vmcnt(11)
	v_mfma_f32_16x16x32_bf16 v[72:75], v[188:191], v[80:83], v[72:75]
	v_mfma_f32_16x16x32_bf16 v[36:39], v[188:191], v[84:87], v[36:39]
	v_mfma_f32_16x16x32_bf16 v[8:11], v[188:191], v[88:91], v[8:11]
	v_mfma_f32_16x16x32_bf16 v[28:31], v[188:191], v[92:95], v[28:31]
	s_waitcnt vmcnt(10)
	v_mfma_f32_16x16x32_bf16 v[72:75], v[192:195], v[96:99], v[72:75]
	v_mfma_f32_16x16x32_bf16 v[36:39], v[192:195], v[100:103], v[36:39]
	v_mfma_f32_16x16x32_bf16 v[8:11], v[192:195], v[104:107], v[8:11]
	v_mfma_f32_16x16x32_bf16 v[28:31], v[192:195], v[168:171], v[28:31]
	s_waitcnt vmcnt(9)
	v_mfma_f32_16x16x32_bf16 v[76:79], v[196:199], v[80:83], v[76:79]
	v_mfma_f32_16x16x32_bf16 v[44:47], v[196:199], v[84:87], v[44:47]
	v_mfma_f32_16x16x32_bf16 v[12:15], v[196:199], v[88:91], v[12:15]
	v_mfma_f32_16x16x32_bf16 v[40:43], v[196:199], v[92:95], v[40:43]
	s_waitcnt vmcnt(4)
	v_mfma_f32_16x16x32_bf16 v[76:79], v[200:203], v[96:99], v[76:79]
	v_mfma_f32_16x16x32_bf16 v[44:47], v[200:203], v[100:103], v[44:47]
	v_mfma_f32_16x16x32_bf16 v[12:15], v[200:203], v[104:107], v[12:15]
	v_mfma_f32_16x16x32_bf16 v[40:43], v[200:203], v[168:171], v[40:43]
	s_waitcnt vmcnt(3)
	v_mfma_f32_16x16x32_bf16 v[64:67], v[204:207], v[80:83], v[64:67]
	v_mfma_f32_16x16x32_bf16 v[20:23], v[204:207], v[84:87], v[20:23]
	v_mfma_f32_16x16x32_bf16 v[0:3], v[204:207], v[88:91], v[0:3]
	v_mfma_f32_16x16x32_bf16 v[16:19], v[204:207], v[92:95], v[16:19]
	s_waitcnt vmcnt(2)
	v_mfma_f32_16x16x32_bf16 v[64:67], v[208:211], v[96:99], v[64:67]
	v_mfma_f32_16x16x32_bf16 v[20:23], v[208:211], v[100:103], v[20:23]
	v_mfma_f32_16x16x32_bf16 v[0:3], v[208:211], v[104:107], v[0:3]
	v_mfma_f32_16x16x32_bf16 v[16:19], v[208:211], v[168:171], v[16:19]
	s_waitcnt vmcnt(1)
	v_mfma_f32_16x16x32_bf16 v[68:71], v[212:215], v[80:83], v[68:71]
	v_mfma_f32_16x16x32_bf16 v[32:35], v[212:215], v[84:87], v[32:35]
	v_mfma_f32_16x16x32_bf16 v[4:7], v[212:215], v[88:91], v[4:7]
	v_mfma_f32_16x16x32_bf16 v[24:27], v[212:215], v[92:95], v[24:27]
	s_waitcnt vmcnt(0)
	v_mfma_f32_16x16x32_bf16 v[68:71], v[216:219], v[96:99], v[68:71]
	v_mfma_f32_16x16x32_bf16 v[32:35], v[216:219], v[100:103], v[32:35]
	v_mfma_f32_16x16x32_bf16 v[4:7], v[216:219], v[104:107], v[4:7]
	v_mfma_f32_16x16x32_bf16 v[24:27], v[216:219], v[168:171], v[24:27]
	s_mov_b64 s[0:1], 0x100
	v_or_b32_e32 v144, 16, v150
	v_or_b32_e32 v160, 32, v150
	v_or_b32_e32 v162, 48, v150
	v_mov_b32_e32 v121, v162
	v_mov_b32_e32 v151, v160
	v_mov_b32_e32 v161, v144
	v_mov_b32_e32 v163, v150
	v_mad_u32_u24 v240, v150, s75, v251
	s_mov_b32 s9, 0
	v_mov_b64_e32 v[164:165], v[140:141]
	v_mov_b32_e32 v250, v241
